# v47 + attention: gate (z) row loads issued at the top of the item's last K/V tile into idle staging regs; staged to LDS before the next item's prefetch; epilogue vmcnt waits removed
# speedup vs baseline: 1.0057x; 1.0036x over previous
; #define LAS __attribute__((address_space(3)))
; __device__ __forceinline__ unsigned pk2(float lo, float hi) { f32x2 v = {lo, hi}; nbf2 r = __builtin_convertvector(v, nbf2); return __builtin_bit_cast(unsigned, r); }
; __device__ __forceinline__ float bf_lo(unsigned w) { return __uint_as_float(w << 16); }
; __device__ __forceinline__ float bf_hi(unsigned w) { return __uint_as_float(w & 0xffff0000u); }
; __device__ __forceinline__ float silu_f(float z) { return z * fast_rcp(1.0f + fast_exp2(-z * LOG2E)); }
; #define WAVE_LDS_FENCE() asm volatile("s_waitcnt lgkmcnt(0)" ::: "memory")
; __device__ __forceinline__ void attn_phase(LAS unsigned char* lds, const bf16_t* QKVZ, bf16_t* AO, const float* sink) {
;     ...
;         WAVE_LDS_FENCE();
; #pragma unroll
;         for (int qt = 0; qt < 2; ++qt) {
;             const auto lr_ = __builtin_amdgcn_permlane32_swap(__float_as_uint(l_[qt]), __float_as_uint(l_[qt]), false, false);
;             const float lt = __uint_as_float(lr_[0]) + __uint_as_float(lr_[1]), inv = 1.0f / lt;
; #pragma unroll
;             for (int dt = 0; dt < 2; ++dt)
; #pragma unroll
;                 for (int a4 = 0; a4 < 4; ++a4) {
;                     LAS u32x2* slot = (LAS u32x2*)(wsc + (32 * qt + ql) * 144 + (32 * dt + 8 * a4 + 4 * hh) * 2);
;                     const u32x2 zw = *slot;
;                     const float o0 = O[dt][qt][4 * a4 + 0] * inv * silu_f(bf_lo(zw.x)), o1 = O[dt][qt][4 * a4 + 1] * inv * silu_f(bf_hi(zw.x));
;                     const float o2 = O[dt][qt][4 * a4 + 2] * inv * silu_f(bf_lo(zw.y)), o3 = O[dt][qt][4 * a4 + 3] * inv * silu_f(bf_hi(zw.y));
;                     u32x2 w; w.x = pk2(o0, o1); w.y = pk2(o2, o3);
;                     *slot = w;
;                 }
;         }
.LBB0_284:
	v_mov_b32_e32 v2, v1
	s_nop 1
	v_permlane32_swap_b32_e32 v1, v2
	v_add_f32_e32 v1, v1, v2
	v_div_scale_f32 v2, s[2:3], v1, v1, 1.0
	v_rcp_f32_e32 v3, v2
	s_waitcnt lgkmcnt(0)
	s_lshl_b32 s0, s67, 6
	v_fma_f32 v4, -v2, v3, 1.0
	v_fmac_f32_e32 v3, v4, v3
	v_div_scale_f32 v4, vcc, 1.0, v1, 1.0
	v_mul_f32_e32 v8, v4, v3
	v_fma_f32 v5, -v2, v8, v4
	v_fmac_f32_e32 v8, v5, v3
	v_fma_f32 v2, -v2, v8, v4
	ds_read2_b64 v[4:7], v225 offset1:2
	v_div_fmas_f32 v2, v2, v3, v8
	v_div_fixup_f32 v2, v2, v1, 1.0
	ds_read2_b64 v[8:11], v225 offset0:4 offset1:6
	v_ashrrev_i32_e32 v15, 31, v14
	s_waitcnt lgkmcnt(1)
	v_lshlrev_b32_e32 v12, 16, v4
	v_mul_f32_e32 v1, 0xbfb8aa3b, v12
	v_and_b32_e32 v13, 0xffff0000, v4
	v_exp_f32_e32 v1, v1
	v_mul_f32_e32 v3, 0xbfb8aa3b, v13
	v_exp_f32_e32 v3, v3
	v_lshlrev_b32_e32 v80, 16, v5
	v_add_f32_e32 v1, 1.0, v1
	v_rcp_f32_e32 v4, v1
	v_pk_mul_f32 v[64:65], v[64:65], v[2:3] op_sel_hi:[1,0]
	v_add_f32_e32 v1, 1.0, v3
	v_and_b32_e32 v81, 0xffff0000, v5
	v_mul_f32_e32 v3, 0xbfb8aa3b, v80
	v_exp_f32_e32 v3, v3
	v_mul_f32_e32 v5, 0xbfb8aa3b, v81
	v_exp_f32_e32 v83, v5
	v_rcp_f32_e32 v5, v1
	v_add_f32_e32 v1, 1.0, v3
	v_rcp_f32_e32 v82, v1
	v_add_f32_e32 v1, 1.0, v83
	v_rcp_f32_e32 v83, v1
	v_pk_mul_f32 v[4:5], v[4:5], v[12:13]
	v_pk_mul_f32 v[12:13], v[66:67], v[2:3] op_sel_hi:[1,0]
	v_pk_mul_f32 v[4:5], v[64:65], v[4:5]
	v_pk_mul_f32 v[64:65], v[82:83], v[80:81]
	v_cvt_pk_bf16_f32 v4, v4, v5
	v_pk_mul_f32 v[12:13], v[12:13], v[64:65]
	v_lshlrev_b32_e32 v66, 16, v7
	v_cvt_pk_bf16_f32 v5, v12, v13
	v_lshlrev_b32_e32 v12, 16, v6
	v_mul_f32_e32 v1, 0xbfb8aa3b, v12
	v_and_b32_e32 v13, 0xffff0000, v6
	v_exp_f32_e32 v1, v1
	v_mul_f32_e32 v3, 0xbfb8aa3b, v13
	v_exp_f32_e32 v3, v3
	v_and_b32_e32 v67, 0xffff0000, v7
	v_add_f32_e32 v1, 1.0, v1
	v_rcp_f32_e32 v6, v1
	v_pk_mul_f32 v[64:65], v[68:69], v[2:3] op_sel_hi:[1,0]
	v_add_f32_e32 v1, 1.0, v3
	v_mul_f32_e32 v3, 0xbfb8aa3b, v66
	v_exp_f32_e32 v3, v3
	v_mul_f32_e32 v7, 0xbfb8aa3b, v67
	v_exp_f32_e32 v69, v7
	v_rcp_f32_e32 v7, v1
	v_add_f32_e32 v1, 1.0, v3
	v_rcp_f32_e32 v68, v1
	v_add_f32_e32 v1, 1.0, v69
	v_rcp_f32_e32 v69, v1
	v_pk_mul_f32 v[6:7], v[6:7], v[12:13]
	v_pk_mul_f32 v[12:13], v[70:71], v[2:3] op_sel_hi:[1,0]
	v_pk_mul_f32 v[6:7], v[64:65], v[6:7]
	v_pk_mul_f32 v[64:65], v[68:69], v[66:67]
	v_cvt_pk_bf16_f32 v6, v6, v7
	v_pk_mul_f32 v[12:13], v[12:13], v[64:65]
	s_lshl_b32 s22, s0, 1
	v_cvt_pk_bf16_f32 v7, v12, v13
	ds_write2_b64 v225, v[4:5], v[6:7] offset1:2
	s_waitcnt lgkmcnt(1)
	v_lshlrev_b32_e32 v4, 16, v8
	v_mul_f32_e32 v1, 0xbfb8aa3b, v4
	v_and_b32_e32 v5, 0xffff0000, v8
	v_exp_f32_e32 v1, v1
	v_mul_f32_e32 v3, 0xbfb8aa3b, v5
	v_exp_f32_e32 v3, v3
	v_lshlrev_b32_e32 v8, 16, v9
	v_add_f32_e32 v1, 1.0, v1
	v_rcp_f32_e32 v6, v1
	v_pk_mul_f32 v[12:13], v[72:73], v[2:3] op_sel_hi:[1,0]
	v_add_f32_e32 v1, 1.0, v3
	v_and_b32_e32 v9, 0xffff0000, v9
	v_mul_f32_e32 v3, 0xbfb8aa3b, v8
	v_exp_f32_e32 v3, v3
	v_mul_f32_e32 v7, 0xbfb8aa3b, v9
	v_exp_f32_e32 v65, v7
	v_rcp_f32_e32 v7, v1
	v_add_f32_e32 v1, 1.0, v3
	v_rcp_f32_e32 v64, v1
	v_add_f32_e32 v1, 1.0, v65
	v_rcp_f32_e32 v65, v1
	v_pk_mul_f32 v[4:5], v[6:7], v[4:5]
	v_pk_mul_f32 v[6:7], v[74:75], v[2:3] op_sel_hi:[1,0]
	v_pk_mul_f32 v[4:5], v[12:13], v[4:5]
	v_pk_mul_f32 v[8:9], v[64:65], v[8:9]
	v_ashrrev_i32_e32 v101, 31, v100
	v_pk_mul_f32 v[6:7], v[6:7], v[8:9]
	v_cvt_pk_bf16_f32 v8, v4, v5
	v_lshlrev_b32_e32 v4, 16, v10
	v_mul_f32_e32 v1, 0xbfb8aa3b, v4
	v_and_b32_e32 v5, 0xffff0000, v10
	v_exp_f32_e32 v1, v1
	v_mul_f32_e32 v3, 0xbfb8aa3b, v5
	v_exp_f32_e32 v3, v3
	v_lshlrev_b32_e32 v10, 16, v11
	v_add_f32_e32 v1, 1.0, v1
	v_cvt_pk_bf16_f32 v9, v6, v7
	v_rcp_f32_e32 v6, v1
	v_pk_mul_f32 v[12:13], v[76:77], v[2:3] op_sel_hi:[1,0]
	v_add_f32_e32 v1, 1.0, v3
	v_and_b32_e32 v11, 0xffff0000, v11
	v_mul_f32_e32 v3, 0xbfb8aa3b, v10
	v_exp_f32_e32 v3, v3
	v_mul_f32_e32 v7, 0xbfb8aa3b, v11
	v_exp_f32_e32 v65, v7
	v_rcp_f32_e32 v7, v1
	v_add_f32_e32 v1, 1.0, v3
	v_rcp_f32_e32 v64, v1
	v_add_f32_e32 v1, 1.0, v65
	v_rcp_f32_e32 v65, v1
	v_pk_mul_f32 v[4:5], v[6:7], v[4:5]
	v_pk_mul_f32 v[66:67], v[78:79], v[2:3] op_sel_hi:[1,0]
	v_pk_mul_f32 v[12:13], v[12:13], v[4:5]
	ds_read2_b64 v[4:7], v225 offset0:8 offset1:10
	v_pk_mul_f32 v[10:11], v[64:65], v[10:11]
	v_cvt_pk_bf16_f32 v12, v12, v13
	v_pk_mul_f32 v[10:11], v[66:67], v[10:11]
	v_ashrrev_i32_e32 v103, 31, v102
	v_cvt_pk_bf16_f32 v13, v10, v11
	ds_write2_b64 v225, v[8:9], v[12:13] offset0:4 offset1:6
	s_waitcnt lgkmcnt(1)
	v_lshlrev_b32_e32 v8, 16, v4
	v_mul_f32_e32 v1, 0xbfb8aa3b, v8
	v_and_b32_e32 v9, 0xffff0000, v4
	v_exp_f32_e32 v1, v1
	v_mul_f32_e32 v3, 0xbfb8aa3b, v9
	v_exp_f32_e32 v3, v3
	v_lshlrev_b32_e32 v12, 16, v5
	v_add_f32_e32 v1, 1.0, v1
	v_rcp_f32_e32 v4, v1
	v_pk_mul_f32 v[10:11], v[48:49], v[2:3] op_sel_hi:[1,0]
	v_add_f32_e32 v1, 1.0, v3
	v_and_b32_e32 v13, 0xffff0000, v5
	v_mul_f32_e32 v3, 0xbfb8aa3b, v12
	v_exp_f32_e32 v3, v3
	v_mul_f32_e32 v5, 0xbfb8aa3b, v13
	v_exp_f32_e32 v49, v5
	v_rcp_f32_e32 v5, v1
	v_add_f32_e32 v1, 1.0, v3
	v_rcp_f32_e32 v48, v1
	v_add_f32_e32 v1, 1.0, v49
	v_rcp_f32_e32 v49, v1
	v_pk_mul_f32 v[4:5], v[4:5], v[8:9]
	v_pk_mul_f32 v[8:9], v[50:51], v[2:3] op_sel_hi:[1,0]
	v_pk_mul_f32 v[4:5], v[10:11], v[4:5]
	v_pk_mul_f32 v[10:11], v[48:49], v[12:13]
	v_lshlrev_b32_e32 v12, 16, v7
	v_pk_mul_f32 v[8:9], v[8:9], v[10:11]
	v_cvt_pk_bf16_f32 v10, v4, v5
	v_lshlrev_b32_e32 v4, 16, v6
	v_mul_f32_e32 v1, 0xbfb8aa3b, v4
	v_and_b32_e32 v5, 0xffff0000, v6
	v_exp_f32_e32 v1, v1
	v_mul_f32_e32 v3, 0xbfb8aa3b, v5
	v_exp_f32_e32 v3, v3
	v_cvt_pk_bf16_f32 v11, v8, v9
	v_add_f32_e32 v1, 1.0, v1
	v_rcp_f32_e32 v6, v1
	v_pk_mul_f32 v[8:9], v[52:53], v[2:3] op_sel_hi:[1,0]
	v_add_f32_e32 v1, 1.0, v3
	v_and_b32_e32 v13, 0xffff0000, v7
	v_mul_f32_e32 v3, 0xbfb8aa3b, v12
	v_exp_f32_e32 v3, v3
	v_mul_f32_e32 v7, 0xbfb8aa3b, v13
	v_exp_f32_e32 v49, v7
	v_rcp_f32_e32 v7, v1
	v_add_f32_e32 v1, 1.0, v3
	v_rcp_f32_e32 v48, v1
	v_add_f32_e32 v1, 1.0, v49
	v_rcp_f32_e32 v49, v1
	v_pk_mul_f32 v[4:5], v[6:7], v[4:5]
	v_pk_mul_f32 v[50:51], v[54:55], v[2:3] op_sel_hi:[1,0]
	v_pk_mul_f32 v[8:9], v[8:9], v[4:5]
	ds_read2_b64 v[4:7], v225 offset0:12 offset1:14
	v_pk_mul_f32 v[12:13], v[48:49], v[12:13]
	v_cvt_pk_bf16_f32 v8, v8, v9
	v_pk_mul_f32 v[12:13], v[50:51], v[12:13]
	v_ashrrev_i32_e32 v105, 31, v104
	v_cvt_pk_bf16_f32 v9, v12, v13
	ds_write2_b64 v225, v[10:11], v[8:9] offset0:8 offset1:10
	s_waitcnt lgkmcnt(1)
; #define LAS __attribute__((address_space(3)))
; __device__ __forceinline__ unsigned pk2(float lo, float hi) { f32x2 v = {lo, hi}; nbf2 r = __builtin_convertvector(v, nbf2); return __builtin_bit_cast(unsigned, r); }
; __device__ __forceinline__ float bf_lo(unsigned w) { return __uint_as_float(w << 16); }
; __device__ __forceinline__ float bf_hi(unsigned w) { return __uint_as_float(w & 0xffff0000u); }
; __device__ __forceinline__ float silu_f(float z) { return z * fast_rcp(1.0f + fast_exp2(-z * LOG2E)); }
; __device__ __forceinline__ void attn_phase(LAS unsigned char* lds, const bf16_t* QKVZ, bf16_t* AO, const float* sink) {
;     ...
;         for (int qt = 0; qt < 2; ++qt) {
;             const auto lr_ = __builtin_amdgcn_permlane32_swap(__float_as_uint(l_[qt]), __float_as_uint(l_[qt]), false, false);
;             const float lt = __uint_as_float(lr_[0]) + __uint_as_float(lr_[1]), inv = 1.0f / lt;
; #pragma unroll
;             for (int dt = 0; dt < 2; ++dt)
; #pragma unroll
;                 for (int a4 = 0; a4 < 4; ++a4) {
;                     LAS u32x2* slot = (LAS u32x2*)(wsc + (32 * qt + ql) * 144 + (32 * dt + 8 * a4 + 4 * hh) * 2);
;                     const u32x2 zw = *slot;
;                     const float o0 = O[dt][qt][4 * a4 + 0] * inv * silu_f(bf_lo(zw.x)), o1 = O[dt][qt][4 * a4 + 1] * inv * silu_f(bf_hi(zw.x));
;                     const float o2 = O[dt][qt][4 * a4 + 2] * inv * silu_f(bf_lo(zw.y)), o3 = O[dt][qt][4 * a4 + 3] * inv * silu_f(bf_hi(zw.y));
;                     u32x2 w; w.x = pk2(o0, o1); w.y = pk2(o2, o3);
;                     *slot = w;
;                 }
;         }
	v_lshlrev_b32_e32 v8, 16, v4
	v_mul_f32_e32 v1, 0xbfb8aa3b, v8
	v_and_b32_e32 v9, 0xffff0000, v4
	v_exp_f32_e32 v1, v1
	v_mul_f32_e32 v3, 0xbfb8aa3b, v9
	v_exp_f32_e32 v3, v3
	v_lshlrev_b32_e32 v12, 16, v5
	v_add_f32_e32 v1, 1.0, v1
	v_rcp_f32_e32 v4, v1
	v_pk_mul_f32 v[10:11], v[56:57], v[2:3] op_sel_hi:[1,0]
	v_add_f32_e32 v1, 1.0, v3
	v_and_b32_e32 v13, 0xffff0000, v5
	v_mul_f32_e32 v3, 0xbfb8aa3b, v12
	v_exp_f32_e32 v3, v3
	v_mul_f32_e32 v5, 0xbfb8aa3b, v13
	v_exp_f32_e32 v49, v5
	v_rcp_f32_e32 v5, v1
	v_add_f32_e32 v1, 1.0, v3
	v_rcp_f32_e32 v48, v1
	v_add_f32_e32 v1, 1.0, v49
	v_rcp_f32_e32 v49, v1
	v_pk_mul_f32 v[4:5], v[4:5], v[8:9]
	v_pk_mul_f32 v[8:9], v[58:59], v[2:3] op_sel_hi:[1,0]
	v_pk_mul_f32 v[4:5], v[10:11], v[4:5]
	v_pk_mul_f32 v[10:11], v[48:49], v[12:13]
	v_cvt_pk_bf16_f32 v4, v4, v5
	v_pk_mul_f32 v[8:9], v[8:9], v[10:11]
	v_lshlrev_b32_e32 v12, 16, v7
	v_cvt_pk_bf16_f32 v5, v8, v9
	v_lshlrev_b32_e32 v8, 16, v6
	v_mul_f32_e32 v1, 0xbfb8aa3b, v8
	v_and_b32_e32 v9, 0xffff0000, v6
	v_exp_f32_e32 v1, v1
	v_mul_f32_e32 v3, 0xbfb8aa3b, v9
	v_exp_f32_e32 v3, v3
	v_and_b32_e32 v13, 0xffff0000, v7
	v_add_f32_e32 v1, 1.0, v1
	v_rcp_f32_e32 v6, v1
	v_pk_mul_f32 v[10:11], v[60:61], v[2:3] op_sel_hi:[1,0]
	v_add_f32_e32 v1, 1.0, v3
	v_mul_f32_e32 v3, 0xbfb8aa3b, v12
	v_exp_f32_e32 v3, v3
	v_mul_f32_e32 v7, 0xbfb8aa3b, v13
	v_exp_f32_e32 v49, v7
	v_rcp_f32_e32 v7, v1
	v_add_f32_e32 v1, 1.0, v3
	v_rcp_f32_e32 v48, v1
	v_add_f32_e32 v1, 1.0, v49
	v_rcp_f32_e32 v49, v1
	v_mov_b32_e32 v1, v227
	s_nop 1
	v_permlane32_swap_b32_e32 v227, v1
	v_pk_mul_f32 v[6:7], v[6:7], v[8:9]
	v_pk_mul_f32 v[2:3], v[62:63], v[2:3] op_sel_hi:[1,0]
	v_pk_mul_f32 v[8:9], v[48:49], v[12:13]
	v_add_f32_e32 v1, v227, v1
	v_pk_mul_f32 v[2:3], v[2:3], v[8:9]
	v_div_scale_f32 v8, s[2:3], v1, v1, 1.0
	v_rcp_f32_e32 v9, v8
	v_pk_mul_f32 v[6:7], v[10:11], v[6:7]
	v_add_u32_e32 v48, 0x1000, v225
	v_cvt_pk_bf16_f32 v6, v6, v7
	v_cvt_pk_bf16_f32 v7, v2, v3
	v_fma_f32 v2, -v8, v9, 1.0
	v_fmac_f32_e32 v9, v2, v9
	v_div_scale_f32 v2, vcc, 1.0, v1, 1.0
	v_mul_f32_e32 v3, v2, v9
	ds_write2_b64 v225, v[4:5], v[6:7] offset0:12 offset1:14
	v_fma_f32 v4, -v8, v3, v2
	v_fmac_f32_e32 v3, v4, v9
	ds_read2_b64 v[4:7], v48 offset0:64 offset1:66
	v_fma_f32 v2, -v8, v3, v2
	v_div_fmas_f32 v2, v2, v9, v3
	v_div_fixup_f32 v2, v2, v1, 1.0
	v_ashrrev_i32_e32 v107, 31, v106
	s_waitcnt lgkmcnt(0)
	v_lshlrev_b32_e32 v8, 16, v4
	v_mul_f32_e32 v1, 0xbfb8aa3b, v8
	v_and_b32_e32 v9, 0xffff0000, v4
	v_exp_f32_e32 v1, v1
	v_mul_f32_e32 v3, 0xbfb8aa3b, v9
	v_exp_f32_e32 v3, v3
	v_lshlrev_b32_e32 v12, 16, v5
	v_add_f32_e32 v1, 1.0, v1
	v_rcp_f32_e32 v4, v1
	v_pk_mul_f32 v[10:11], v[32:33], v[2:3] op_sel_hi:[1,0]
	v_add_f32_e32 v1, 1.0, v3
	v_and_b32_e32 v13, 0xffff0000, v5
	v_mul_f32_e32 v3, 0xbfb8aa3b, v12
	v_exp_f32_e32 v3, v3
	v_mul_f32_e32 v5, 0xbfb8aa3b, v13
	v_exp_f32_e32 v33, v5
	v_rcp_f32_e32 v5, v1
	v_add_f32_e32 v1, 1.0, v3
	v_rcp_f32_e32 v32, v1
	v_add_f32_e32 v1, 1.0, v33
	v_rcp_f32_e32 v33, v1
	v_pk_mul_f32 v[4:5], v[4:5], v[8:9]
	v_pk_mul_f32 v[8:9], v[34:35], v[2:3] op_sel_hi:[1,0]
	v_pk_mul_f32 v[4:5], v[10:11], v[4:5]
	v_pk_mul_f32 v[10:11], v[32:33], v[12:13]
	v_lshlrev_b32_e32 v12, 16, v7
	v_pk_mul_f32 v[8:9], v[8:9], v[10:11]
	v_cvt_pk_bf16_f32 v10, v4, v5
	v_lshlrev_b32_e32 v4, 16, v6
	v_mul_f32_e32 v1, 0xbfb8aa3b, v4
	v_and_b32_e32 v5, 0xffff0000, v6
	v_exp_f32_e32 v1, v1
	v_mul_f32_e32 v3, 0xbfb8aa3b, v5
	v_exp_f32_e32 v3, v3
	v_cvt_pk_bf16_f32 v11, v8, v9
	v_add_f32_e32 v1, 1.0, v1
	v_rcp_f32_e32 v6, v1
	v_pk_mul_f32 v[8:9], v[36:37], v[2:3] op_sel_hi:[1,0]
	v_add_f32_e32 v1, 1.0, v3
	v_and_b32_e32 v13, 0xffff0000, v7
	v_mul_f32_e32 v3, 0xbfb8aa3b, v12
	v_exp_f32_e32 v3, v3
	v_mul_f32_e32 v7, 0xbfb8aa3b, v13
	v_exp_f32_e32 v33, v7
	v_rcp_f32_e32 v7, v1
	v_add_f32_e32 v1, 1.0, v3
	v_rcp_f32_e32 v32, v1
	v_add_f32_e32 v1, 1.0, v33
	v_rcp_f32_e32 v33, v1
	v_pk_mul_f32 v[4:5], v[6:7], v[4:5]
	v_pk_mul_f32 v[34:35], v[38:39], v[2:3] op_sel_hi:[1,0]
	v_pk_mul_f32 v[8:9], v[8:9], v[4:5]
	ds_read2_b64 v[4:7], v48 offset0:68 offset1:70
	v_pk_mul_f32 v[12:13], v[32:33], v[12:13]
	v_cvt_pk_bf16_f32 v8, v8, v9
	v_pk_mul_f32 v[12:13], v[34:35], v[12:13]
	v_ashrrev_i32_e32 v109, 31, v108
	v_cvt_pk_bf16_f32 v9, v12, v13
	ds_write2_b64 v48, v[10:11], v[8:9] offset0:64 offset1:66
	s_waitcnt lgkmcnt(1)
	v_lshlrev_b32_e32 v8, 16, v4
	v_mul_f32_e32 v1, 0xbfb8aa3b, v8
	v_and_b32_e32 v9, 0xffff0000, v4
	v_exp_f32_e32 v1, v1
	v_mul_f32_e32 v3, 0xbfb8aa3b, v9
	v_exp_f32_e32 v3, v3
	v_lshlrev_b32_e32 v12, 16, v5
	v_add_f32_e32 v1, 1.0, v1
	v_rcp_f32_e32 v4, v1
	v_pk_mul_f32 v[10:11], v[40:41], v[2:3] op_sel_hi:[1,0]
	v_add_f32_e32 v1, 1.0, v3
	v_and_b32_e32 v13, 0xffff0000, v5
	v_mul_f32_e32 v3, 0xbfb8aa3b, v12
	v_exp_f32_e32 v3, v3
	v_mul_f32_e32 v5, 0xbfb8aa3b, v13
	v_exp_f32_e32 v33, v5
	v_rcp_f32_e32 v5, v1
	v_add_f32_e32 v1, 1.0, v3
	v_rcp_f32_e32 v32, v1
	v_add_f32_e32 v1, 1.0, v33
	v_rcp_f32_e32 v33, v1
	v_pk_mul_f32 v[4:5], v[4:5], v[8:9]
	v_pk_mul_f32 v[8:9], v[42:43], v[2:3] op_sel_hi:[1,0]
	v_pk_mul_f32 v[4:5], v[10:11], v[4:5]
	v_pk_mul_f32 v[10:11], v[32:33], v[12:13]
	v_lshlrev_b32_e32 v12, 16, v7
	v_pk_mul_f32 v[8:9], v[8:9], v[10:11]
	v_cvt_pk_bf16_f32 v10, v4, v5
	v_lshlrev_b32_e32 v4, 16, v6
	v_mul_f32_e32 v1, 0xbfb8aa3b, v4
	v_and_b32_e32 v5, 0xffff0000, v6
	v_exp_f32_e32 v1, v1
	v_mul_f32_e32 v3, 0xbfb8aa3b, v5
	v_exp_f32_e32 v3, v3
	v_cvt_pk_bf16_f32 v11, v8, v9
	v_add_f32_e32 v1, 1.0, v1
	v_rcp_f32_e32 v6, v1
	v_pk_mul_f32 v[8:9], v[44:45], v[2:3] op_sel_hi:[1,0]
	v_add_f32_e32 v1, 1.0, v3
	v_and_b32_e32 v13, 0xffff0000, v7
	v_mul_f32_e32 v3, 0xbfb8aa3b, v12
	v_exp_f32_e32 v3, v3
	v_mul_f32_e32 v7, 0xbfb8aa3b, v13
	v_exp_f32_e32 v33, v7
	v_rcp_f32_e32 v7, v1
	v_add_f32_e32 v1, 1.0, v3
	v_rcp_f32_e32 v32, v1
	v_add_f32_e32 v1, 1.0, v33
	v_rcp_f32_e32 v33, v1
	v_pk_mul_f32 v[4:5], v[6:7], v[4:5]
	v_pk_mul_f32 v[34:35], v[46:47], v[2:3] op_sel_hi:[1,0]
	v_pk_mul_f32 v[8:9], v[8:9], v[4:5]
	ds_read2_b64 v[4:7], v48 offset0:72 offset1:74
	v_pk_mul_f32 v[12:13], v[32:33], v[12:13]
	v_cvt_pk_bf16_f32 v8, v8, v9
	v_pk_mul_f32 v[12:13], v[34:35], v[12:13]
	v_ashrrev_i32_e32 v113, 31, v112
	v_cvt_pk_bf16_f32 v9, v12, v13
	ds_write2_b64 v48, v[10:11], v[8:9] offset0:68 offset1:70
	s_waitcnt lgkmcnt(1)
; #define LAS __attribute__((address_space(3)))
; __device__ __forceinline__ unsigned pk2(float lo, float hi) { f32x2 v = {lo, hi}; nbf2 r = __builtin_convertvector(v, nbf2); return __builtin_bit_cast(unsigned, r); }
; __device__ __forceinline__ float bf_lo(unsigned w) { return __uint_as_float(w << 16); }
; __device__ __forceinline__ float bf_hi(unsigned w) { return __uint_as_float(w & 0xffff0000u); }
; __device__ __forceinline__ float silu_f(float z) { return z * fast_rcp(1.0f + fast_exp2(-z * LOG2E)); }
; #define WAVE_LDS_FENCE() asm volatile("s_waitcnt lgkmcnt(0)" ::: "memory")
; __device__ __forceinline__ void attn_phase(LAS unsigned char* lds, const bf16_t* QKVZ, bf16_t* AO, const float* sink) {
;     ...
;         for (int qt = 0; qt < 2; ++qt) {
;             const auto lr_ = __builtin_amdgcn_permlane32_swap(__float_as_uint(l_[qt]), __float_as_uint(l_[qt]), false, false);
;             const float lt = __uint_as_float(lr_[0]) + __uint_as_float(lr_[1]), inv = 1.0f / lt;
; #pragma unroll
;             for (int dt = 0; dt < 2; ++dt)
; #pragma unroll
;                 for (int a4 = 0; a4 < 4; ++a4) {
;                     LAS u32x2* slot = (LAS u32x2*)(wsc + (32 * qt + ql) * 144 + (32 * dt + 8 * a4 + 4 * hh) * 2);
;                     const u32x2 zw = *slot;
;                     const float o0 = O[dt][qt][4 * a4 + 0] * inv * silu_f(bf_lo(zw.x)), o1 = O[dt][qt][4 * a4 + 1] * inv * silu_f(bf_hi(zw.x));
;                     const float o2 = O[dt][qt][4 * a4 + 2] * inv * silu_f(bf_lo(zw.y)), o3 = O[dt][qt][4 * a4 + 3] * inv * silu_f(bf_hi(zw.y));
;                     u32x2 w; w.x = pk2(o0, o1); w.y = pk2(o2, o3);
;                     *slot = w;
;                 }
;         }
;         WAVE_LDS_FENCE();
; #pragma unroll
;         for (int it = 0; it < 8; ++it) *(u32x4*)(AO + (size_t)(qrow0 + 64 * qh + er + 8 * it) * D + head * 64 + 8 * ec) = *(const LAS u32x4*)(wsc + (er + 8 * it) * 144 + ec * 16);
	v_lshlrev_b32_e32 v8, 16, v4
	v_mul_f32_e32 v1, 0xbfb8aa3b, v8
	v_and_b32_e32 v9, 0xffff0000, v4
	v_exp_f32_e32 v1, v1
	v_mul_f32_e32 v3, 0xbfb8aa3b, v9
	v_exp_f32_e32 v3, v3
	v_lshlrev_b32_e32 v12, 16, v5
	v_add_f32_e32 v1, 1.0, v1
	v_rcp_f32_e32 v4, v1
	v_pk_mul_f32 v[10:11], v[16:17], v[2:3] op_sel_hi:[1,0]
	v_add_f32_e32 v1, 1.0, v3
	v_and_b32_e32 v13, 0xffff0000, v5
	v_mul_f32_e32 v3, 0xbfb8aa3b, v12
	v_exp_f32_e32 v3, v3
	v_mul_f32_e32 v5, 0xbfb8aa3b, v13
	v_exp_f32_e32 v17, v5
	v_rcp_f32_e32 v5, v1
	v_add_f32_e32 v1, 1.0, v3
	v_rcp_f32_e32 v16, v1
	v_add_f32_e32 v1, 1.0, v17
	v_rcp_f32_e32 v17, v1
	v_pk_mul_f32 v[4:5], v[4:5], v[8:9]
	v_pk_mul_f32 v[8:9], v[18:19], v[2:3] op_sel_hi:[1,0]
	v_pk_mul_f32 v[4:5], v[10:11], v[4:5]
	v_pk_mul_f32 v[10:11], v[16:17], v[12:13]
	v_lshlrev_b32_e32 v12, 16, v7
	v_pk_mul_f32 v[8:9], v[8:9], v[10:11]
	v_cvt_pk_bf16_f32 v10, v4, v5
	v_lshlrev_b32_e32 v4, 16, v6
	v_mul_f32_e32 v1, 0xbfb8aa3b, v4
	v_and_b32_e32 v5, 0xffff0000, v6
	v_exp_f32_e32 v1, v1
	v_mul_f32_e32 v3, 0xbfb8aa3b, v5
	v_exp_f32_e32 v3, v3
	v_cvt_pk_bf16_f32 v11, v8, v9
	v_add_f32_e32 v1, 1.0, v1
	v_rcp_f32_e32 v6, v1
	v_pk_mul_f32 v[8:9], v[20:21], v[2:3] op_sel_hi:[1,0]
	v_add_f32_e32 v1, 1.0, v3
	v_and_b32_e32 v13, 0xffff0000, v7
	v_mul_f32_e32 v3, 0xbfb8aa3b, v12
	v_exp_f32_e32 v3, v3
	v_mul_f32_e32 v7, 0xbfb8aa3b, v13
	v_exp_f32_e32 v17, v7
	v_rcp_f32_e32 v7, v1
	v_add_f32_e32 v1, 1.0, v3
	v_rcp_f32_e32 v16, v1
	v_add_f32_e32 v1, 1.0, v17
	v_rcp_f32_e32 v17, v1
	v_pk_mul_f32 v[4:5], v[6:7], v[4:5]
	v_pk_mul_f32 v[18:19], v[22:23], v[2:3] op_sel_hi:[1,0]
	v_pk_mul_f32 v[8:9], v[8:9], v[4:5]
	ds_read2_b64 v[4:7], v48 offset0:76 offset1:78
	v_pk_mul_f32 v[12:13], v[16:17], v[12:13]
	v_cvt_pk_bf16_f32 v8, v8, v9
	v_pk_mul_f32 v[12:13], v[18:19], v[12:13]
	v_ashrrev_i32_e32 v111, 31, v110
	v_cvt_pk_bf16_f32 v9, v12, v13
	ds_write2_b64 v48, v[10:11], v[8:9] offset0:72 offset1:74
	s_waitcnt lgkmcnt(1)
	v_lshlrev_b32_e32 v8, 16, v4
	v_mul_f32_e32 v1, 0xbfb8aa3b, v8
	v_and_b32_e32 v9, 0xffff0000, v4
	v_exp_f32_e32 v1, v1
	v_mul_f32_e32 v3, 0xbfb8aa3b, v9
	v_exp_f32_e32 v3, v3
	v_lshlrev_b32_e32 v12, 16, v5
	v_add_f32_e32 v1, 1.0, v1
	v_rcp_f32_e32 v4, v1
	v_pk_mul_f32 v[10:11], v[24:25], v[2:3] op_sel_hi:[1,0]
	v_add_f32_e32 v1, 1.0, v3
	v_and_b32_e32 v13, 0xffff0000, v5
	v_mul_f32_e32 v3, 0xbfb8aa3b, v12
	v_exp_f32_e32 v3, v3
	v_mul_f32_e32 v5, 0xbfb8aa3b, v13
	v_exp_f32_e32 v17, v5
	v_rcp_f32_e32 v5, v1
	v_add_f32_e32 v1, 1.0, v3
	v_rcp_f32_e32 v16, v1
	v_add_f32_e32 v1, 1.0, v17
	v_rcp_f32_e32 v17, v1
	v_pk_mul_f32 v[4:5], v[4:5], v[8:9]
	v_pk_mul_f32 v[8:9], v[26:27], v[2:3] op_sel_hi:[1,0]
	v_pk_mul_f32 v[4:5], v[10:11], v[4:5]
	v_pk_mul_f32 v[10:11], v[16:17], v[12:13]
	v_cvt_pk_bf16_f32 v4, v4, v5
	v_pk_mul_f32 v[8:9], v[8:9], v[10:11]
	v_lshlrev_b32_e32 v12, 16, v7
	v_cvt_pk_bf16_f32 v5, v8, v9
	v_lshlrev_b32_e32 v8, 16, v6
	v_mul_f32_e32 v1, 0xbfb8aa3b, v8
	v_and_b32_e32 v9, 0xffff0000, v6
	v_exp_f32_e32 v1, v1
	v_mul_f32_e32 v3, 0xbfb8aa3b, v9
	v_exp_f32_e32 v3, v3
	v_and_b32_e32 v13, 0xffff0000, v7
	v_add_f32_e32 v1, 1.0, v1
	v_rcp_f32_e32 v6, v1
	v_pk_mul_f32 v[10:11], v[28:29], v[2:3] op_sel_hi:[1,0]
	v_add_f32_e32 v1, 1.0, v3
	v_mul_f32_e32 v3, 0xbfb8aa3b, v12
	v_exp_f32_e32 v3, v3
	v_mul_f32_e32 v7, 0xbfb8aa3b, v13
	v_exp_f32_e32 v17, v7
	v_rcp_f32_e32 v7, v1
	v_add_f32_e32 v1, 1.0, v3
	v_rcp_f32_e32 v16, v1
	v_add_f32_e32 v1, 1.0, v17
	v_rcp_f32_e32 v17, v1
	v_pk_mul_f32 v[6:7], v[6:7], v[8:9]
	v_pk_mul_f32 v[2:3], v[30:31], v[2:3] op_sel_hi:[1,0]
	v_pk_mul_f32 v[6:7], v[10:11], v[6:7]
	v_pk_mul_f32 v[8:9], v[16:17], v[12:13]
	v_cvt_pk_bf16_f32 v6, v6, v7
	v_pk_mul_f32 v[2:3], v[2:3], v[8:9]
	v_lshl_add_u64 v[10:11], v[198:199], 0, s[22:23]
	v_cvt_pk_bf16_f32 v7, v2, v3
	ds_write2_b64 v48, v[4:5], v[6:7] offset0:76 offset1:78
	s_waitcnt lgkmcnt(0)
	ds_read_b128 v[2:5], v224
	v_lshlrev_b64 v[6:7], 11, v[14:15]
	v_lshl_add_u64 v[12:13], v[10:11], 0, v[6:7]
	ds_read_b128 v[6:9], v224 offset:1152
	s_cmp_lg_u32 s24, s56
	s_waitcnt lgkmcnt(1)
	global_store_dwordx4 v[12:13], v[2:5], off
	s_mov_b32 s66, s24
	s_nop 0
	v_lshlrev_b64 v[2:3], 11, v[100:101]
	v_lshl_add_u64 v[12:13], v[10:11], 0, v[2:3]
	ds_read_b128 v[2:5], v224 offset:2304
	s_waitcnt lgkmcnt(1)
	global_store_dwordx4 v[12:13], v[6:9], off
	s_nop 1
	v_lshlrev_b64 v[6:7], 11, v[102:103]
	v_lshl_add_u64 v[12:13], v[10:11], 0, v[6:7]
	ds_read_b128 v[6:9], v224 offset:3456
	s_waitcnt lgkmcnt(1)
	global_store_dwordx4 v[12:13], v[2:5], off
	s_nop 1
	v_lshlrev_b64 v[2:3], 11, v[104:105]
	v_lshl_add_u64 v[12:13], v[10:11], 0, v[2:3]
	ds_read_b128 v[2:5], v224 offset:4608
	s_waitcnt lgkmcnt(1)
	global_store_dwordx4 v[12:13], v[6:9], off
	s_nop 1
	v_lshlrev_b64 v[6:7], 11, v[106:107]
	v_lshl_add_u64 v[12:13], v[10:11], 0, v[6:7]
	ds_read_b128 v[6:9], v224 offset:5760
	s_waitcnt lgkmcnt(1)
	global_store_dwordx4 v[12:13], v[2:5], off
	s_nop 1
	v_lshlrev_b64 v[2:3], 11, v[108:109]
	v_lshl_add_u64 v[12:13], v[10:11], 0, v[2:3]
	ds_read_b128 v[2:5], v224 offset:6912
	s_waitcnt lgkmcnt(1)
	global_store_dwordx4 v[12:13], v[6:9], off
	ds_read_b128 v[6:9], v224 offset:8064
	v_lshlrev_b64 v[12:13], 11, v[112:113]
	v_lshl_add_u64 v[12:13], v[10:11], 0, v[12:13]
	s_waitcnt lgkmcnt(1)
	global_store_dwordx4 v[12:13], v[2:5], off
	s_nop 1
	v_lshlrev_b64 v[2:3], 11, v[110:111]
	v_lshl_add_u64 v[2:3], v[10:11], 0, v[2:3]
	s_waitcnt lgkmcnt(0)
	global_store_dwordx4 v[2:3], v[6:9], off
	s_waitcnt lgkmcnt(0)
	s_cbranch_scc0 .LBB0_377

; __device__ __forceinline__ void attn_phase(LAS unsigned char* lds, const bf16_t* QKVZ, bf16_t* AO, const float* sink) {
;     ...
;             if (tnext < ntiles) {
;                 const int krow0 = isctx ? NLAT + b * CTXL + tnext * 128 : (tnext < 3 ? b * SEQ + (nblk - 1 + tnext) * 128 : NLAT + b * CTXL + (tnext - 3) * 128);
; #pragma unroll
;                 for (int i = 0; i < 2; ++i) { const int c = tid + 512 * i, key = c >> 3, dc = c & 7; kr[i] = *(const u32x4*)(QKVZ + (size_t)(krow0 + key) * NQKVZ + 1024 + kh * 64 + dc * 8); }
;                 va = *(const u32x4*)(QKVZ + (size_t)(krow0 + 2 * kp) * NQKVZ + 1280 + kh * 64 + dcv * 8);
;                 vb = *(const u32x4*)(QKVZ + (size_t)(krow0 + 2 * kp + 1) * NQKVZ + 1280 + kh * 64 + dcv * 8);
;     ...
; #pragma unroll
;         for (int it = 0; it < 8; ++it) zt[it] = *(const u32x4*)(QKVZ + (size_t)(qrow0 + 64 * qh + er + 8 * it) * NQKVZ + 1536 + head * 64 + 8 * ec);
.LBB0_307:
	v_add_u32_e32 v8, v6, v195
	v_mad_i64_i32 v[10:11], s[0:1], v8, s63, v[2:3]
	v_add_u32_e32 v8, v6, v220
	v_add_u32_e32 v6, v6, v217
	v_mad_i64_i32 v[12:13], s[0:1], v8, s63, v[2:3]
	global_load_dwordx4 v[176:179], v[10:11], off offset:2048
	global_load_dwordx4 v[180:183], v[12:13], off offset:2048
	v_mad_i64_i32 v[10:11], s[0:1], v6, s63, v[4:5]
	v_add_u32_e32 v6, 1, v6
	v_mad_i64_i32 v[12:13], s[0:1], v6, s63, v[4:5]
	global_load_dwordx4 v[184:187], v[10:11], off offset:2560
	global_load_dwordx4 v[188:191], v[12:13], off offset:2560
	s_branch .LBB0_308
.Lattn_gate_pf:
	v_add_u32_e32 v180, s70, v218
	v_mov_b64_e32 v[182:183], s[18:19]
	s_lshl_b32 s96, s67, 7
	s_mov_b32 s97, 0
	s_lshl_b32 s98, s63, 3
	s_mov_b32 s99, 0
	v_mad_i64_i32 v[176:177], s[0:1], v180, s63, v[182:183]
	v_mov_b32_e32 v182, v204
	v_mov_b32_e32 v183, 0
	v_lshl_add_u64 v[176:177], v[176:177], 0, s[96:97]
	v_lshl_add_u64 v[176:177], v[176:177], 0, v[182:183]
	v_lshl_add_u64 v[180:181], v[176:177], 0, s[98:99]
	v_lshl_add_u64 v[184:185], v[180:181], 0, s[98:99]
	v_lshl_add_u64 v[188:189], v[184:185], 0, s[98:99]
	v_lshl_add_u64 v[240:241], v[188:189], 0, s[98:99]
	v_lshl_add_u64 v[244:245], v[240:241], 0, s[98:99]
	v_lshl_add_u64 v[248:249], v[244:245], 0, s[98:99]
	v_lshl_add_u64 v[252:253], v[248:249], 0, s[98:99]
	global_load_dwordx4 v[176:179], v[176:177], off offset:3072
	global_load_dwordx4 v[180:183], v[180:181], off offset:3072
	global_load_dwordx4 v[184:187], v[184:185], off offset:3072
	global_load_dwordx4 v[188:191], v[188:189], off offset:3072
	global_load_dwordx4 v[240:243], v[240:241], off offset:3072
	global_load_dwordx4 v[244:247], v[244:245], off offset:3072
	global_load_dwordx4 v[248:251], v[248:249], off offset:3072
	global_load_dwordx4 v[252:255], v[252:253], off offset:3072

; #define LAS __attribute__((address_space(3)))
; #define ATT_LOADQ(Q, it) do { const int qr0_ = ATT_QROW0(it), hd_ = ((it) & 3) * 4 + hq; _Pragma("unroll") for (int qt = 0; qt < 2; ++qt) _Pragma("unroll") for (int ks = 0; ks < 4; ++ks) \
;         Q[qt][ks] = *(const bf16x8*)(QKVZ + (size_t)(qr0_ + 64 * qh + 32 * qt + ql) * NQKVZ + hd_ * 64 + 16 * ks + 8 * hh); } while (0)
; __device__ __forceinline__ void attn_phase(LAS unsigned char* lds, const bf16_t* QKVZ, bf16_t* AO, const float* sink) {
;     ...
;         LAS unsigned char* wsc = lds + 2 * ATT_BUF + wave * 9216;
;         const int er = lane >> 3, ec = lane & 7;
;         u32x4 zt[8];
; #pragma unroll
;         for (int it = 0; it < 8; ++it) zt[it] = *(const u32x4*)(QKVZ + (size_t)(qrow0 + 64 * qh + er + 8 * it) * NQKVZ + 1536 + head * 64 + 8 * ec);
;         if (k + 1 < nit) { ATT_LOADQ(Qn, ATT_ITEM(k + 1)); ATT_LOADKV0(ATT_ITEM(k + 1)); }
; #pragma unroll
;         for (int it = 0; it < 8; ++it) *(LAS u32x4*)(wsc + (er + 8 * it) * 144 + ec * 16) = zt[it];
.LBB0_321:
	v_add_u32_e32 v14, s70, v218
	v_add_u32_e32 v100, 8, v14
	v_add_u32_e32 v102, 16, v14
	v_add_u32_e32 v104, 24, v14
	v_add_u32_e32 v106, 32, v14
	v_add_u32_e32 v108, 40, v14
	v_add_u32_e32 v112, 48, v14
	v_add_u32_e32 v110, 56, v14
	v_mov_b32_e32 v205, v0
	s_lshl_b32 s22, s67, 7
	s_waitcnt vmcnt(0)
	ds_write_b128 v224, v[176:179]
	ds_write_b128 v224, v[180:183] offset:1152
	ds_write_b128 v224, v[184:187] offset:2304
	ds_write_b128 v224, v[188:191] offset:3456
	ds_write_b128 v224, v[240:243] offset:4608
	ds_write_b128 v224, v[244:247] offset:5760
	ds_write_b128 v224, v[248:251] offset:6912
	ds_write_b128 v224, v[252:255] offset:8064
	s_add_i32 s24, s66, 1
	s_cmp_ge_i32 s24, s56
	s_cbranch_scc1 .LBB0_284
	s_mov_b64 s[0:1], -1
	s_and_b64 vcc, exec, s[8:9]
	s_mul_i32 s25, s24, s14
	s_cbranch_vccz .LBB0_324
	s_add_i32 s2, s25, s12
	s_cbranch_execnz .LBB0_326
	s_branch .LBB0_325
